# early-barrier variant: finishing wave at priority 2 for its tail MFMAs, starting wave raises to priority 1 immediately
# baseline (speedup 1.0000x reference)
; #define PG8_STAGE(bufoff, gbase, voff) do { _Pragma("unroll") for (int _i = 0; _i < 2; ++_i) \
;         __builtin_amdgcn_global_load_lds((const unsigned*)((const char*)(gbase) + (voff)[_i]), (PG8_LAS unsigned*)(lds + (bufoff) + ldsw + _i * 8192), 16, 0, 0); } while (0)
; #define PG8_LDA(dst, b, h) do { _Pragma("unroll") for (int m = 0; m < 4; ++m) _Pragma("unroll") for (int k = 0; k < 2; ++k) dst[m][k] = *(const PG8_LAS bf16x8*)(lds + PG8_SA(b, h) + aoff + m * 2048 + k * 1024); } while (0)
; #define PG8_LDB(dst, b, h) do { _Pragma("unroll") for (int n = 0; n < 2; ++n) _Pragma("unroll") for (int k = 0; k < 2; ++k) dst[n][k] = *(const PG8_LAS bf16x8*)(lds + PG8_SB(b, h) + boff + n * 2048 + k * 1024); } while (0)
; #define PG8_MMA(ai, bj, At, Bt) do { __builtin_amdgcn_s_setprio(1); _Pragma("unroll") for (int m = 0; m < 4; ++m) _Pragma("unroll") for (int n = 0; n < 2; ++n) _Pragma("unroll") for (int k = 0; k < 2; ++k) \
;         acc[ai][bj][m][n] = __builtin_amdgcn_mfma_f32_16x16x32_bf16(Bt[n][k], At[m][k], acc[ai][bj][m][n], 0, 0, 0); __builtin_amdgcn_s_setprio(0); } while (0)
; #define PG8_WAIT_V(n) asm volatile("s_waitcnt vmcnt(" #n ")" ::: "memory")
; #define PG8_WAIT_L(n) asm volatile("s_waitcnt lgkmcnt(" #n ")" ::: "memory")
; #define PG8_BAR __builtin_amdgcn_s_barrier()
; #define PG8_SCHED __builtin_amdgcn_sched_barrier(0)
; template <class Epi, class Sched, bool ALIGN_EPI = false, bool SP2 = false>
; __device__ __forceinline__ void gemm_phase(PG8_LAS unsigned char* lds, const Gemm g, const Sched& S, const Epi& E) {
;     ...
;             PG8_LDB(B0, 0, 0); PG8_LDB(B1, 0, 1); PG8_SCHED; PG8_LDA(At, 0, 0); PG8_STAGE(PG8_SA(1, 1), a1 + hstep, voffA);
;             PG8_WAIT_V(8); PG8_WAIT_L(0); PG8_BAR; PG8_MMA(0, 0, At, B0); PG8_MMA(0, 1, At, B1); PG8_BAR; PG8_SCHED;
;             PG8_LDA(At, 0, 1); PG8_STAGE(PG8_SB(0, 0), b2, voffB); PG8_STAGE(PG8_SB(0, 1), b2 + hstep, voffB); PG8_STAGE(PG8_SA(0, 0), a2, voffA);
;             PG8_WAIT_V(8); PG8_WAIT_L(0); PG8_BAR; PG8_MMA(1, 0, At, B0); PG8_MMA(1, 1, At, B1); PG8_BAR; PG8_SCHED;
.LBB0_165:
	s_add_i32 s18, 0, 0x10000
	v_add_u32_e32 v0, s18, v194
	s_add_i32 s19, 0, 0x14000
	ds_read_b128 v[136:139], v0
	ds_read_b128 v[140:143], v0 offset:1024
	ds_read_b128 v[144:147], v0 offset:2048
	ds_read_b128 v[148:151], v0 offset:3072
	v_add_u32_e32 v0, s19, v194
	ds_read_b128 v[152:155], v0
	ds_read_b128 v[186:189], v0 offset:1024
	ds_read_b128 v[190:193], v0 offset:2048
	ds_read_b128 v[198:201], v0 offset:3072
	v_lshl_add_u64 v[2:3], s[8:9], 0, v[182:183]
	s_add_i32 m0, s45, 0xc000
	ds_read_b128 v[210:213], v196
	ds_read_b128 v[214:217], v196 offset:1024
	ds_read_b128 v[218:221], v196 offset:2048
	ds_read_b128 v[222:225], v196 offset:3072
	ds_read_b128 v[226:229], v196 offset:4096
	ds_read_b128 v[230:233], v196 offset:5120
	ds_read_b128 v[234:237], v196 offset:6144
	ds_read_b128 v[238:241], v196 offset:7168
	global_load_lds_dwordx4 v[2:3], off
	v_lshl_add_u64 v[2:3], s[8:9], 0, v[184:185]
	s_add_i32 m0, s45, 0xe000
	s_nop 0
	global_load_lds_dwordx4 v[2:3], off
	s_waitcnt vmcnt(8)
	s_waitcnt lgkmcnt(0)
	s_barrier
	s_setprio 1
	s_waitcnt lgkmcnt(0)
	v_mfma_f32_16x16x32_bf16 v[132:135], v[136:139], v[210:213], v[132:135]
	v_mfma_f32_16x16x32_bf16 v[128:131], v[144:147], v[210:213], v[128:131]
	v_mfma_f32_16x16x32_bf16 v[124:127], v[136:139], v[218:221], v[124:127]
	v_mfma_f32_16x16x32_bf16 v[120:123], v[144:147], v[218:221], v[120:123]
	v_mfma_f32_16x16x32_bf16 v[116:119], v[136:139], v[226:229], v[116:119]
	v_mfma_f32_16x16x32_bf16 v[112:115], v[144:147], v[226:229], v[112:115]
	v_mfma_f32_16x16x32_bf16 v[108:111], v[136:139], v[234:237], v[108:111]
	v_mfma_f32_16x16x32_bf16 v[104:107], v[144:147], v[234:237], v[104:107]
	v_mfma_f32_16x16x32_bf16 v[132:135], v[140:143], v[214:217], v[132:135]
	v_mfma_f32_16x16x32_bf16 v[128:131], v[148:151], v[214:217], v[128:131]
	v_mfma_f32_16x16x32_bf16 v[124:127], v[140:143], v[222:225], v[124:127]
	v_mfma_f32_16x16x32_bf16 v[120:123], v[148:151], v[222:225], v[120:123]
	v_mfma_f32_16x16x32_bf16 v[116:119], v[140:143], v[230:233], v[116:119]
	v_mfma_f32_16x16x32_bf16 v[112:115], v[148:151], v[230:233], v[112:115]
	v_mfma_f32_16x16x32_bf16 v[108:111], v[140:143], v[238:241], v[108:111]
	v_mfma_f32_16x16x32_bf16 v[104:107], v[148:151], v[238:241], v[104:107]
	s_setprio 0
	s_setprio 1
	v_mfma_f32_16x16x32_bf16 v[84:87], v[152:155], v[210:213], v[84:87]
	v_mfma_f32_16x16x32_bf16 v[76:79], v[190:193], v[210:213], v[76:79]
	v_mfma_f32_16x16x32_bf16 v[68:71], v[152:155], v[218:221], v[68:71]
	v_mfma_f32_16x16x32_bf16 v[64:67], v[190:193], v[218:221], v[64:67]
	v_mfma_f32_16x16x32_bf16 v[52:55], v[152:155], v[226:229], v[52:55]
	v_mfma_f32_16x16x32_bf16 v[48:51], v[190:193], v[226:229], v[48:51]
	v_mfma_f32_16x16x32_bf16 v[44:47], v[152:155], v[234:237], v[44:47]
	v_mfma_f32_16x16x32_bf16 v[40:43], v[190:193], v[234:237], v[40:43]
	v_mfma_f32_16x16x32_bf16 v[84:87], v[186:189], v[214:217], v[84:87]
	v_mfma_f32_16x16x32_bf16 v[76:79], v[198:201], v[214:217], v[76:79]
	v_mfma_f32_16x16x32_bf16 v[68:71], v[186:189], v[222:225], v[68:71]
	v_mfma_f32_16x16x32_bf16 v[64:67], v[198:201], v[222:225], v[64:67]
	s_setprio 2
	s_barrier
	v_mfma_f32_16x16x32_bf16 v[52:55], v[186:189], v[230:233], v[52:55]
	v_mfma_f32_16x16x32_bf16 v[48:51], v[198:201], v[230:233], v[48:51]
	v_mfma_f32_16x16x32_bf16 v[44:47], v[186:189], v[238:241], v[44:47]
	v_mfma_f32_16x16x32_bf16 v[40:43], v[198:201], v[238:241], v[40:43]
	s_setprio 0
	s_add_i32 s16, s18, s44
	v_lshl_add_u64 v[2:3], s[40:41], 0, v[162:163]
	s_mov_b32 m0, s16
	ds_read_b128 v[210:213], v196 offset:16384
	ds_read_b128 v[214:217], v196 offset:17408
	ds_read_b128 v[218:221], v196 offset:18432
	ds_read_b128 v[222:225], v196 offset:19456
	ds_read_b128 v[226:229], v196 offset:20480
	ds_read_b128 v[230:233], v196 offset:21504
	ds_read_b128 v[234:237], v196 offset:22528
	ds_read_b128 v[238:241], v196 offset:23552
	global_load_lds_dwordx4 v[2:3], off
	s_add_i32 m0, s16, 0x2000
	s_add_u32 s16, s40, 0x40000
	v_lshl_add_u64 v[156:157], s[40:41], 0, v[158:159]
	s_addc_u32 s17, s41, 0
	s_add_i32 s18, s19, s44
	global_load_lds_dwordx4 v[156:157], off
	v_lshl_add_u64 v[242:243], s[16:17], 0, v[162:163]
	s_mov_b32 m0, s18
	v_lshl_add_u64 v[244:245], s[42:43], 0, v[160:161]
	global_load_lds_dwordx4 v[242:243], off
	v_lshl_add_u64 v[242:243], s[16:17], 0, v[158:159]
	s_add_i32 m0, s18, 0x2000
	s_nop 0
	global_load_lds_dwordx4 v[242:243], off
	v_lshl_add_u64 v[242:243], s[42:43], 0, v[178:179]
	s_waitcnt vmcnt(6)
	s_waitcnt lgkmcnt(0)
	s_barrier
	s_setprio 1
	s_waitcnt lgkmcnt(0)
	v_mfma_f32_16x16x32_bf16 v[100:103], v[136:139], v[210:213], v[100:103]
	v_mfma_f32_16x16x32_bf16 v[96:99], v[144:147], v[210:213], v[96:99]
	v_mfma_f32_16x16x32_bf16 v[92:95], v[136:139], v[218:221], v[92:95]
	s_mov_b32 m0, s45
	v_mfma_f32_16x16x32_bf16 v[88:91], v[144:147], v[218:221], v[88:91]
	global_load_lds_dwordx4 v[242:243], off
	v_mfma_f32_16x16x32_bf16 v[80:83], v[136:139], v[226:229], v[80:83]
	v_mfma_f32_16x16x32_bf16 v[72:75], v[144:147], v[226:229], v[72:75]
	v_mfma_f32_16x16x32_bf16 v[60:63], v[136:139], v[234:237], v[60:63]
	v_mfma_f32_16x16x32_bf16 v[56:59], v[144:147], v[234:237], v[56:59]
	v_mfma_f32_16x16x32_bf16 v[100:103], v[140:143], v[214:217], v[100:103]
	v_mfma_f32_16x16x32_bf16 v[96:99], v[148:151], v[214:217], v[96:99]
	v_mfma_f32_16x16x32_bf16 v[92:95], v[140:143], v[222:225], v[92:95]
	s_mov_b32 m0, s46
	v_mfma_f32_16x16x32_bf16 v[88:91], v[148:151], v[222:225], v[88:91]
	global_load_lds_dwordx4 v[244:245], off
	v_mfma_f32_16x16x32_bf16 v[80:83], v[140:143], v[230:233], v[80:83]
	v_mfma_f32_16x16x32_bf16 v[72:75], v[148:151], v[230:233], v[72:75]
	v_mfma_f32_16x16x32_bf16 v[60:63], v[140:143], v[238:241], v[60:63]
	v_mfma_f32_16x16x32_bf16 v[56:59], v[148:151], v[238:241], v[56:59]
	s_setprio 0
	s_setprio 1
	v_mfma_f32_16x16x32_bf16 v[36:39], v[152:155], v[210:213], v[36:39]
	v_mfma_f32_16x16x32_bf16 v[32:35], v[190:193], v[210:213], v[32:35]
	v_mfma_f32_16x16x32_bf16 v[28:31], v[152:155], v[218:221], v[28:31]
	v_mfma_f32_16x16x32_bf16 v[24:27], v[190:193], v[218:221], v[24:27]
	v_mfma_f32_16x16x32_bf16 v[20:23], v[152:155], v[226:229], v[20:23]
	v_mfma_f32_16x16x32_bf16 v[16:19], v[190:193], v[226:229], v[16:19]
	v_mfma_f32_16x16x32_bf16 v[12:15], v[152:155], v[234:237], v[12:15]
	v_mfma_f32_16x16x32_bf16 v[8:11], v[190:193], v[234:237], v[8:11]
	v_mfma_f32_16x16x32_bf16 v[36:39], v[186:189], v[214:217], v[36:39]
	v_mfma_f32_16x16x32_bf16 v[32:35], v[198:201], v[214:217], v[32:35]
	v_mfma_f32_16x16x32_bf16 v[28:31], v[186:189], v[222:225], v[28:31]
	v_mfma_f32_16x16x32_bf16 v[24:27], v[198:201], v[222:225], v[24:27]
	s_setprio 2
	s_barrier
; #define PG8_STAGE(bufoff, gbase, voff) do { _Pragma("unroll") for (int _i = 0; _i < 2; ++_i) \
;         __builtin_amdgcn_global_load_lds((const unsigned*)((const char*)(gbase) + (voff)[_i]), (PG8_LAS unsigned*)(lds + (bufoff) + ldsw + _i * 8192), 16, 0, 0); } while (0)
; #define PG8_LDA(dst, b, h) do { _Pragma("unroll") for (int m = 0; m < 4; ++m) _Pragma("unroll") for (int k = 0; k < 2; ++k) dst[m][k] = *(const PG8_LAS bf16x8*)(lds + PG8_SA(b, h) + aoff + m * 2048 + k * 1024); } while (0)
; #define PG8_LDB(dst, b, h) do { _Pragma("unroll") for (int n = 0; n < 2; ++n) _Pragma("unroll") for (int k = 0; k < 2; ++k) dst[n][k] = *(const PG8_LAS bf16x8*)(lds + PG8_SB(b, h) + boff + n * 2048 + k * 1024); } while (0)
; #define PG8_MMA(ai, bj, At, Bt) do { __builtin_amdgcn_s_setprio(1); _Pragma("unroll") for (int m = 0; m < 4; ++m) _Pragma("unroll") for (int n = 0; n < 2; ++n) _Pragma("unroll") for (int k = 0; k < 2; ++k) \
;         acc[ai][bj][m][n] = __builtin_amdgcn_mfma_f32_16x16x32_bf16(Bt[n][k], At[m][k], acc[ai][bj][m][n], 0, 0, 0); __builtin_amdgcn_s_setprio(0); } while (0)
; #define PG8_WAIT_V(n) asm volatile("s_waitcnt vmcnt(" #n ")" ::: "memory")
; #define PG8_WAIT_L(n) asm volatile("s_waitcnt lgkmcnt(" #n ")" ::: "memory")
; #define PG8_BAR __builtin_amdgcn_s_barrier()
; #define PG8_SCHED __builtin_amdgcn_sched_barrier(0)
; template <class Epi, class Sched, bool ALIGN_EPI = false, bool SP2 = false>
; __device__ __forceinline__ void gemm_phase(PG8_LAS unsigned char* lds, const Gemm g, const Sched& S, const Epi& E) {
;     ...
;             PG8_WAIT_V(8); PG8_WAIT_L(0); PG8_BAR; PG8_MMA(1, 0, At, B0); PG8_MMA(1, 1, At, B1); PG8_BAR; PG8_SCHED;
;             PG8_LDB(B0, 1, 0); PG8_LDB(B1, 1, 1); PG8_SCHED; PG8_LDA(At, 1, 0); PG8_STAGE(PG8_SA(0, 1), a2 + hstep, voffA);
;             PG8_WAIT_V(8); PG8_WAIT_L(0); PG8_BAR; PG8_MMA(0, 0, At, B0); PG8_MMA(0, 1, At, B1); PG8_BAR; PG8_SCHED;
	v_mfma_f32_16x16x32_bf16 v[20:23], v[186:189], v[230:233], v[20:23]
	v_mfma_f32_16x16x32_bf16 v[16:19], v[198:201], v[230:233], v[16:19]
	v_mfma_f32_16x16x32_bf16 v[12:15], v[186:189], v[238:241], v[12:15]
	v_mfma_f32_16x16x32_bf16 v[8:11], v[198:201], v[238:241], v[8:11]
	s_setprio 0
	s_add_i32 s18, 0, 0x18000
	v_add_u32_e32 v0, s18, v194
	ds_read_b128 v[136:139], v0
	ds_read_b128 v[140:143], v0 offset:1024
	ds_read_b128 v[144:147], v0 offset:2048
	ds_read_b128 v[148:151], v0 offset:3072
	v_add_u32_e32 v0, s33, v194
	ds_read_b128 v[152:155], v0
	ds_read_b128 v[186:189], v0 offset:1024
	ds_read_b128 v[190:193], v0 offset:2048
	ds_read_b128 v[198:201], v0 offset:3072
	s_add_u32 s16, s42, 0x40000
	s_addc_u32 s17, s43, 0
	s_mov_b32 m0, s47
	v_lshl_add_u64 v[246:247], s[16:17], 0, v[178:179]
	ds_read_b128 v[210:213], v196 offset:32768
	ds_read_b128 v[214:217], v196 offset:33792
	ds_read_b128 v[218:221], v196 offset:34816
	ds_read_b128 v[222:225], v196 offset:35840
	ds_read_b128 v[226:229], v196 offset:36864
	ds_read_b128 v[230:233], v196 offset:37888
	ds_read_b128 v[234:237], v196 offset:38912
	ds_read_b128 v[238:241], v196 offset:39936
	global_load_lds_dwordx4 v[246:247], off
	v_lshl_add_u64 v[246:247], s[16:17], 0, v[160:161]
	s_mov_b32 m0, s48
	s_nop 0
	global_load_lds_dwordx4 v[246:247], off
	s_waitcnt vmcnt(8)
	s_waitcnt lgkmcnt(0)
	s_barrier
	s_setprio 1
	s_waitcnt lgkmcnt(0)
	v_mfma_f32_16x16x32_bf16 v[132:135], v[136:139], v[210:213], v[132:135]
	v_mfma_f32_16x16x32_bf16 v[128:131], v[144:147], v[210:213], v[128:131]
	v_mfma_f32_16x16x32_bf16 v[124:127], v[136:139], v[218:221], v[124:127]
	v_mfma_f32_16x16x32_bf16 v[120:123], v[144:147], v[218:221], v[120:123]
	v_mfma_f32_16x16x32_bf16 v[116:119], v[136:139], v[226:229], v[116:119]
	v_mfma_f32_16x16x32_bf16 v[112:115], v[144:147], v[226:229], v[112:115]
	v_mfma_f32_16x16x32_bf16 v[108:111], v[136:139], v[234:237], v[108:111]
	v_mfma_f32_16x16x32_bf16 v[104:107], v[144:147], v[234:237], v[104:107]
	v_mfma_f32_16x16x32_bf16 v[132:135], v[140:143], v[214:217], v[132:135]
	v_mfma_f32_16x16x32_bf16 v[128:131], v[148:151], v[214:217], v[128:131]
	v_mfma_f32_16x16x32_bf16 v[124:127], v[140:143], v[222:225], v[124:127]
	v_mfma_f32_16x16x32_bf16 v[120:123], v[148:151], v[222:225], v[120:123]
	v_mfma_f32_16x16x32_bf16 v[116:119], v[140:143], v[230:233], v[116:119]
	v_mfma_f32_16x16x32_bf16 v[112:115], v[148:151], v[230:233], v[112:115]
	v_mfma_f32_16x16x32_bf16 v[108:111], v[140:143], v[238:241], v[108:111]
	v_mfma_f32_16x16x32_bf16 v[104:107], v[148:151], v[238:241], v[104:107]
	s_setprio 0
	s_setprio 1
	v_mfma_f32_16x16x32_bf16 v[84:87], v[152:155], v[210:213], v[84:87]
	v_mfma_f32_16x16x32_bf16 v[76:79], v[190:193], v[210:213], v[76:79]
	v_mfma_f32_16x16x32_bf16 v[68:71], v[152:155], v[218:221], v[68:71]
	v_mfma_f32_16x16x32_bf16 v[64:67], v[190:193], v[218:221], v[64:67]
	v_mfma_f32_16x16x32_bf16 v[52:55], v[152:155], v[226:229], v[52:55]
	v_mfma_f32_16x16x32_bf16 v[48:51], v[190:193], v[226:229], v[48:51]
	v_mfma_f32_16x16x32_bf16 v[44:47], v[152:155], v[234:237], v[44:47]
	v_mfma_f32_16x16x32_bf16 v[40:43], v[190:193], v[234:237], v[40:43]
	v_mfma_f32_16x16x32_bf16 v[84:87], v[186:189], v[214:217], v[84:87]
	v_mfma_f32_16x16x32_bf16 v[76:79], v[198:201], v[214:217], v[76:79]
	v_mfma_f32_16x16x32_bf16 v[68:71], v[186:189], v[222:225], v[68:71]
	v_mfma_f32_16x16x32_bf16 v[64:67], v[198:201], v[222:225], v[64:67]
	s_setprio 2
	s_barrier
; #define PG8_STAGE(bufoff, gbase, voff) do { _Pragma("unroll") for (int _i = 0; _i < 2; ++_i) \
;         __builtin_amdgcn_global_load_lds((const unsigned*)((const char*)(gbase) + (voff)[_i]), (PG8_LAS unsigned*)(lds + (bufoff) + ldsw + _i * 8192), 16, 0, 0); } while (0)
; #define PG8_LDA(dst, b, h) do { _Pragma("unroll") for (int m = 0; m < 4; ++m) _Pragma("unroll") for (int k = 0; k < 2; ++k) dst[m][k] = *(const PG8_LAS bf16x8*)(lds + PG8_SA(b, h) + aoff + m * 2048 + k * 1024); } while (0)
; #define PG8_MMA(ai, bj, At, Bt) do { __builtin_amdgcn_s_setprio(1); _Pragma("unroll") for (int m = 0; m < 4; ++m) _Pragma("unroll") for (int n = 0; n < 2; ++n) _Pragma("unroll") for (int k = 0; k < 2; ++k) \
;         acc[ai][bj][m][n] = __builtin_amdgcn_mfma_f32_16x16x32_bf16(Bt[n][k], At[m][k], acc[ai][bj][m][n], 0, 0, 0); __builtin_amdgcn_s_setprio(0); } while (0)
; #define PG8_WAIT_V(n) asm volatile("s_waitcnt vmcnt(" #n ")" ::: "memory")
; #define PG8_WAIT_L(n) asm volatile("s_waitcnt lgkmcnt(" #n ")" ::: "memory")
; #define PG8_BAR __builtin_amdgcn_s_barrier()
; #define PG8_SCHED __builtin_amdgcn_sched_barrier(0)
; template <class Epi, class Sched, bool ALIGN_EPI = false, bool SP2 = false>
; __device__ __forceinline__ void gemm_phase(PG8_LAS unsigned char* lds, const Gemm g, const Sched& S, const Epi& E) {
;     ...
;         for (int t = 0; t < nt; t += 2) {
;             const bool last = (t == nt - 2);
;             const char* a1 = cA + (size_t)(t + 1) * kstep;
;             const char* a2 = last ? nA : cA + (size_t)(t + 2) * kstep; const char* b2 = last ? nB : cB + (size_t)(t + 2) * kstep;
;             const char* a3 = a2 + kstep; const char* b3 = b2 + kstep;
;     ...
;             PG8_WAIT_V(8); PG8_WAIT_L(0); PG8_BAR; PG8_MMA(0, 0, At, B0); PG8_MMA(0, 1, At, B1); PG8_BAR; PG8_SCHED;
;             PG8_LDA(At, 1, 1); PG8_STAGE(PG8_SB(1, 0), b3, voffB); PG8_STAGE(PG8_SB(1, 1), b3 + hstep, voffB); PG8_STAGE(PG8_SA(1, 0), a3, voffA);
;             PG8_WAIT_V(8); PG8_WAIT_L(0); PG8_BAR; PG8_MMA(1, 0, At, B0); PG8_MMA(1, 1, At, B1); PG8_BAR; PG8_SCHED;
	v_mfma_f32_16x16x32_bf16 v[52:55], v[186:189], v[230:233], v[52:55]
	v_mfma_f32_16x16x32_bf16 v[48:51], v[198:201], v[230:233], v[48:51]
	v_mfma_f32_16x16x32_bf16 v[44:47], v[186:189], v[238:241], v[44:47]
	v_mfma_f32_16x16x32_bf16 v[40:43], v[198:201], v[238:241], v[40:43]
	s_setprio 0
	s_add_i32 s16, s18, s44
	v_lshl_add_u64 v[2:3], v[2:3], 0, s[20:21]
	s_mov_b32 m0, s16
	ds_read_b128 v[210:213], v196 offset:49152
	ds_read_b128 v[214:217], v196 offset:50176
	ds_read_b128 v[218:221], v196 offset:51200
	ds_read_b128 v[222:225], v196 offset:52224
	ds_read_b128 v[226:229], v196 offset:53248
	ds_read_b128 v[230:233], v196 offset:54272
	ds_read_b128 v[234:237], v196 offset:55296
	ds_read_b128 v[238:241], v196 offset:56320
	global_load_lds_dwordx4 v[2:3], off
	s_add_i32 m0, s16, 0x2000
	s_add_u32 s16, s40, 0x40080
	v_lshl_add_u64 v[2:3], v[156:157], 0, s[20:21]
	s_addc_u32 s17, s41, 0
	s_add_i32 s18, s33, s44
	global_load_lds_dwordx4 v[2:3], off
	v_lshl_add_u64 v[2:3], s[16:17], 0, v[162:163]
	s_mov_b32 m0, s18
	s_nop 0
	global_load_lds_dwordx4 v[2:3], off
	v_lshl_add_u64 v[2:3], s[16:17], 0, v[158:159]
	s_add_i32 m0, s18, 0x2000
	s_nop 0
	global_load_lds_dwordx4 v[2:3], off
	v_lshl_add_u64 v[2:3], v[242:243], 0, s[20:21]
	v_lshl_add_u64 v[244:245], v[244:245], 0, s[20:21]
	s_waitcnt vmcnt(6)
	s_waitcnt lgkmcnt(0)
	s_barrier
	s_setprio 1
	s_waitcnt lgkmcnt(0)
	v_mfma_f32_16x16x32_bf16 v[100:103], v[136:139], v[210:213], v[100:103]
	v_mfma_f32_16x16x32_bf16 v[96:99], v[144:147], v[210:213], v[96:99]
	v_mfma_f32_16x16x32_bf16 v[92:95], v[136:139], v[218:221], v[92:95]
	s_mov_b32 m0, s49
	v_mfma_f32_16x16x32_bf16 v[88:91], v[144:147], v[218:221], v[88:91]
	global_load_lds_dwordx4 v[2:3], off
	v_mfma_f32_16x16x32_bf16 v[80:83], v[136:139], v[226:229], v[80:83]
	v_mfma_f32_16x16x32_bf16 v[72:75], v[144:147], v[226:229], v[72:75]
	v_mfma_f32_16x16x32_bf16 v[60:63], v[136:139], v[234:237], v[60:63]
	s_add_i32 s55, s55, 2
	v_mfma_f32_16x16x32_bf16 v[56:59], v[144:147], v[234:237], v[56:59]
	s_add_u32 s8, s8, 0x100
	s_addc_u32 s9, s9, 0
	v_mfma_f32_16x16x32_bf16 v[100:103], v[140:143], v[214:217], v[100:103]
	s_add_u32 s53, s53, 0x100
	s_addc_u32 s54, s54, 0
	v_mfma_f32_16x16x32_bf16 v[96:99], v[148:151], v[214:217], v[96:99]
	s_add_u32 s16, s8, 0xfffc0080
	s_addc_u32 s17, s9, -1
	v_mfma_f32_16x16x32_bf16 v[92:95], v[140:143], v[222:225], v[92:95]
	s_cmp_eq_u32 s55, 12
	s_cselect_b32 s43, s14, s17
	s_cselect_b32 s42, s15, s16
	s_mov_b32 m0, s50
	v_mfma_f32_16x16x32_bf16 v[88:91], v[148:151], v[222:225], v[88:91]
	s_cselect_b32 s41, s13, s54
	s_cselect_b32 s40, s25, s53
	global_load_lds_dwordx4 v[244:245], off
	v_mfma_f32_16x16x32_bf16 v[80:83], v[140:143], v[230:233], v[80:83]
	v_mfma_f32_16x16x32_bf16 v[72:75], v[148:151], v[230:233], v[72:75]
	v_mfma_f32_16x16x32_bf16 v[60:63], v[140:143], v[238:241], v[60:63]
	v_mfma_f32_16x16x32_bf16 v[56:59], v[148:151], v[238:241], v[56:59]
	s_setprio 0
	s_setprio 1
	v_mfma_f32_16x16x32_bf16 v[36:39], v[152:155], v[210:213], v[36:39]
	v_mfma_f32_16x16x32_bf16 v[32:35], v[190:193], v[210:213], v[32:35]
	v_mfma_f32_16x16x32_bf16 v[28:31], v[152:155], v[218:221], v[28:31]
	v_mfma_f32_16x16x32_bf16 v[24:27], v[190:193], v[218:221], v[24:27]
	v_mfma_f32_16x16x32_bf16 v[20:23], v[152:155], v[226:229], v[20:23]
	v_mfma_f32_16x16x32_bf16 v[16:19], v[190:193], v[226:229], v[16:19]
	v_mfma_f32_16x16x32_bf16 v[12:15], v[152:155], v[234:237], v[12:15]
	v_mfma_f32_16x16x32_bf16 v[8:11], v[190:193], v[234:237], v[8:11]
	v_mfma_f32_16x16x32_bf16 v[36:39], v[186:189], v[214:217], v[36:39]
	v_mfma_f32_16x16x32_bf16 v[32:35], v[198:201], v[214:217], v[32:35]
	v_mfma_f32_16x16x32_bf16 v[28:31], v[186:189], v[222:225], v[28:31]
	v_mfma_f32_16x16x32_bf16 v[24:27], v[198:201], v[222:225], v[24:27]
	s_setprio 2
	s_barrier
	v_mfma_f32_16x16x32_bf16 v[20:23], v[186:189], v[230:233], v[20:23]
	v_mfma_f32_16x16x32_bf16 v[16:19], v[198:201], v[230:233], v[16:19]
	v_mfma_f32_16x16x32_bf16 v[12:15], v[186:189], v[238:241], v[12:15]
	v_mfma_f32_16x16x32_bf16 v[8:11], v[198:201], v[238:241], v[8:11]
	s_setprio 0
	s_cmp_gt_u32 s55, 13
	s_cbranch_scc0 .LBB0_165
	s_and_b64 vcc, exec, s[10:11]
	s_cbranch_vccz .LBB0_168
	s_barrier
	s_setprio 1

; #define PG8_STAGE(bufoff, gbase, voff) do { _Pragma("unroll") for (int _i = 0; _i < 2; ++_i) \
;         __builtin_amdgcn_global_load_lds((const unsigned*)((const char*)(gbase) + (voff)[_i]), (PG8_LAS unsigned*)(lds + (bufoff) + ldsw + _i * 8192), 16, 0, 0); } while (0)
; #define PG8_LDA(dst, b, h) do { _Pragma("unroll") for (int m = 0; m < 4; ++m) _Pragma("unroll") for (int k = 0; k < 2; ++k) dst[m][k] = *(const PG8_LAS bf16x8*)(lds + PG8_SA(b, h) + aoff + m * 2048 + k * 1024); } while (0)
; #define PG8_LDB(dst, b, h) do { _Pragma("unroll") for (int n = 0; n < 2; ++n) _Pragma("unroll") for (int k = 0; k < 2; ++k) dst[n][k] = *(const PG8_LAS bf16x8*)(lds + PG8_SB(b, h) + boff + n * 2048 + k * 1024); } while (0)
; #define PG8_MMA(ai, bj, At, Bt) do { __builtin_amdgcn_s_setprio(1); _Pragma("unroll") for (int m = 0; m < 4; ++m) _Pragma("unroll") for (int n = 0; n < 2; ++n) _Pragma("unroll") for (int k = 0; k < 2; ++k) \
;         acc[ai][bj][m][n] = __builtin_amdgcn_mfma_f32_16x16x32_bf16(Bt[n][k], At[m][k], acc[ai][bj][m][n], 0, 0, 0); __builtin_amdgcn_s_setprio(0); } while (0)
; #define PG8_WAIT_V(n) asm volatile("s_waitcnt vmcnt(" #n ")" ::: "memory")
; #define PG8_WAIT_L(n) asm volatile("s_waitcnt lgkmcnt(" #n ")" ::: "memory")
; #define PG8_BAR __builtin_amdgcn_s_barrier()
; #define PG8_SCHED __builtin_amdgcn_sched_barrier(0)
; template <class Epi, class Sched, bool ALIGN_EPI = false, bool SP2 = false>
; __device__ __forceinline__ void gemm_phase(PG8_LAS unsigned char* lds, const Gemm g, const Sched& S, const Epi& E) {
;     ...
;             PG8_LDB(B0, 0, 0); PG8_LDB(B1, 0, 1); PG8_SCHED; PG8_LDA(At, 0, 0); PG8_STAGE(PG8_SA(1, 1), a1 + hstep, voffA);
;             PG8_WAIT_V(8); PG8_WAIT_L(0); PG8_BAR; PG8_MMA(0, 0, At, B0); PG8_MMA(0, 1, At, B1); PG8_BAR; PG8_SCHED;
;             PG8_LDA(At, 0, 1); PG8_STAGE(PG8_SB(0, 0), b2, voffB); PG8_STAGE(PG8_SB(0, 1), b2 + hstep, voffB); PG8_STAGE(PG8_SA(0, 0), a2, voffA);
;             PG8_WAIT_V(8); PG8_WAIT_L(0); PG8_BAR; PG8_MMA(1, 0, At, B0); PG8_MMA(1, 1, At, B1); PG8_BAR; PG8_SCHED;
.LBB0_203:
	s_add_i32 s18, 0, 0x10000
	v_add_u32_e32 v137, s18, v200
	s_add_i32 s19, 0, 0x14000
	ds_read_b128 v[144:147], v137
	ds_read_b128 v[148:151], v137 offset:1024
	ds_read_b128 v[152:155], v137 offset:2048
	ds_read_b128 v[156:159], v137 offset:3072
	v_add_u32_e32 v137, s19, v200
	ds_read_b128 v[160:163], v137
	ds_read_b128 v[178:181], v137 offset:1024
	ds_read_b128 v[182:185], v137 offset:2048
	ds_read_b128 v[186:189], v137 offset:3072
	v_lshl_add_u64 v[198:199], s[24:25], 0, v[140:141]
	s_add_i32 m0, s52, 0xc000
	ds_read_b128 v[190:193], v210
	ds_read_b128 v[194:197], v210 offset:1024
	ds_read_b128 v[212:215], v210 offset:2048
	ds_read_b128 v[216:219], v210 offset:3072
	ds_read_b128 v[220:223], v210 offset:4096
	ds_read_b128 v[224:227], v210 offset:5120
	ds_read_b128 v[228:231], v210 offset:6144
	ds_read_b128 v[232:235], v210 offset:7168
	global_load_lds_dwordx4 v[198:199], off
	v_lshl_add_u64 v[198:199], s[24:25], 0, v[142:143]
	s_add_i32 m0, s52, 0xe000
	s_nop 0
	global_load_lds_dwordx4 v[198:199], off
	s_waitcnt vmcnt(8)
	s_waitcnt lgkmcnt(0)
	s_barrier
	s_setprio 1
	s_waitcnt lgkmcnt(0)
	v_mfma_f32_16x16x32_bf16 v[132:135], v[144:147], v[190:193], v[132:135]
	v_mfma_f32_16x16x32_bf16 v[128:131], v[152:155], v[190:193], v[128:131]
	v_mfma_f32_16x16x32_bf16 v[116:119], v[144:147], v[212:215], v[116:119]
	v_mfma_f32_16x16x32_bf16 v[112:115], v[152:155], v[212:215], v[112:115]
	v_mfma_f32_16x16x32_bf16 v[100:103], v[144:147], v[220:223], v[100:103]
	v_mfma_f32_16x16x32_bf16 v[96:99], v[152:155], v[220:223], v[96:99]
	v_mfma_f32_16x16x32_bf16 v[84:87], v[144:147], v[228:231], v[84:87]
	v_mfma_f32_16x16x32_bf16 v[80:83], v[152:155], v[228:231], v[80:83]
	v_mfma_f32_16x16x32_bf16 v[132:135], v[148:151], v[194:197], v[132:135]
	v_mfma_f32_16x16x32_bf16 v[128:131], v[156:159], v[194:197], v[128:131]
	v_mfma_f32_16x16x32_bf16 v[116:119], v[148:151], v[216:219], v[116:119]
	v_mfma_f32_16x16x32_bf16 v[112:115], v[156:159], v[216:219], v[112:115]
	v_mfma_f32_16x16x32_bf16 v[100:103], v[148:151], v[224:227], v[100:103]
	v_mfma_f32_16x16x32_bf16 v[96:99], v[156:159], v[224:227], v[96:99]
	v_mfma_f32_16x16x32_bf16 v[84:87], v[148:151], v[232:235], v[84:87]
	v_mfma_f32_16x16x32_bf16 v[80:83], v[156:159], v[232:235], v[80:83]
	s_setprio 0
	s_setprio 1
	v_mfma_f32_16x16x32_bf16 v[124:127], v[160:163], v[190:193], v[124:127]
	v_mfma_f32_16x16x32_bf16 v[120:123], v[182:185], v[190:193], v[120:123]
	v_mfma_f32_16x16x32_bf16 v[108:111], v[160:163], v[212:215], v[108:111]
	v_mfma_f32_16x16x32_bf16 v[104:107], v[182:185], v[212:215], v[104:107]
	v_mfma_f32_16x16x32_bf16 v[92:95], v[160:163], v[220:223], v[92:95]
	v_mfma_f32_16x16x32_bf16 v[88:91], v[182:185], v[220:223], v[88:91]
	v_mfma_f32_16x16x32_bf16 v[76:79], v[160:163], v[228:231], v[76:79]
	v_mfma_f32_16x16x32_bf16 v[72:75], v[182:185], v[228:231], v[72:75]
	v_mfma_f32_16x16x32_bf16 v[124:127], v[178:181], v[194:197], v[124:127]
	v_mfma_f32_16x16x32_bf16 v[120:123], v[186:189], v[194:197], v[120:123]
	v_mfma_f32_16x16x32_bf16 v[108:111], v[178:181], v[216:219], v[108:111]
	v_mfma_f32_16x16x32_bf16 v[104:107], v[186:189], v[216:219], v[104:107]
	s_setprio 2
	s_barrier
	v_mfma_f32_16x16x32_bf16 v[92:95], v[178:181], v[224:227], v[92:95]
	v_mfma_f32_16x16x32_bf16 v[88:91], v[186:189], v[224:227], v[88:91]
	v_mfma_f32_16x16x32_bf16 v[76:79], v[178:181], v[232:235], v[76:79]
	v_mfma_f32_16x16x32_bf16 v[72:75], v[186:189], v[232:235], v[72:75]
	s_setprio 0
	s_add_i32 s18, s18, s41
	v_lshl_add_u64 v[198:199], s[16:17], 0, v[0:1]
	s_mov_b32 m0, s18
	ds_read_b128 v[190:193], v210 offset:16384
	ds_read_b128 v[194:197], v210 offset:17408
	ds_read_b128 v[212:215], v210 offset:18432
	ds_read_b128 v[216:219], v210 offset:19456
	ds_read_b128 v[220:223], v210 offset:20480
	ds_read_b128 v[224:227], v210 offset:21504
	ds_read_b128 v[228:231], v210 offset:22528
	ds_read_b128 v[232:235], v210 offset:23552
	global_load_lds_dwordx4 v[198:199], off
	s_add_i32 m0, s18, 0x2000
	v_lshl_add_u64 v[236:237], s[16:17], 0, v[2:3]
	s_add_u32 s16, s16, s12
	s_addc_u32 s17, s17, 0
	s_add_i32 s18, s19, s41
	global_load_lds_dwordx4 v[236:237], off
	v_lshl_add_u64 v[238:239], s[16:17], 0, v[0:1]
	s_mov_b32 m0, s18
	v_lshl_add_u64 v[240:241], s[16:17], 0, v[2:3]
	global_load_lds_dwordx4 v[238:239], off
	s_add_i32 m0, s18, 0x2000
	v_lshl_add_u64 v[242:243], s[28:29], 0, v[0:1]
	global_load_lds_dwordx4 v[240:241], off
	v_lshl_add_u64 v[244:245], s[28:29], 0, v[2:3]
	s_waitcnt vmcnt(6)
	s_waitcnt lgkmcnt(0)
	s_barrier
	s_setprio 1
	s_waitcnt lgkmcnt(0)
	v_mfma_f32_16x16x32_bf16 v[68:71], v[144:147], v[190:193], v[68:71]
	v_mfma_f32_16x16x32_bf16 v[64:67], v[152:155], v[190:193], v[64:67]
	v_mfma_f32_16x16x32_bf16 v[52:55], v[144:147], v[212:215], v[52:55]
	s_mov_b32 m0, s52
	v_mfma_f32_16x16x32_bf16 v[48:51], v[152:155], v[212:215], v[48:51]
	global_load_lds_dwordx4 v[242:243], off
	v_mfma_f32_16x16x32_bf16 v[36:39], v[144:147], v[220:223], v[36:39]
	v_mfma_f32_16x16x32_bf16 v[32:35], v[152:155], v[220:223], v[32:35]
	v_mfma_f32_16x16x32_bf16 v[20:23], v[144:147], v[228:231], v[20:23]
	v_mfma_f32_16x16x32_bf16 v[16:19], v[152:155], v[228:231], v[16:19]
	v_mfma_f32_16x16x32_bf16 v[68:71], v[148:151], v[194:197], v[68:71]
	v_mfma_f32_16x16x32_bf16 v[64:67], v[156:159], v[194:197], v[64:67]
	v_mfma_f32_16x16x32_bf16 v[52:55], v[148:151], v[216:219], v[52:55]
	s_mov_b32 m0, s53
	v_mfma_f32_16x16x32_bf16 v[48:51], v[156:159], v[216:219], v[48:51]
	global_load_lds_dwordx4 v[244:245], off
	v_mfma_f32_16x16x32_bf16 v[36:39], v[148:151], v[224:227], v[36:39]
	v_mfma_f32_16x16x32_bf16 v[32:35], v[156:159], v[224:227], v[32:35]
	v_mfma_f32_16x16x32_bf16 v[20:23], v[148:151], v[232:235], v[20:23]
	v_mfma_f32_16x16x32_bf16 v[16:19], v[156:159], v[232:235], v[16:19]
	s_setprio 0
	s_setprio 1
	v_mfma_f32_16x16x32_bf16 v[60:63], v[160:163], v[190:193], v[60:63]
	v_mfma_f32_16x16x32_bf16 v[56:59], v[182:185], v[190:193], v[56:59]
	v_mfma_f32_16x16x32_bf16 v[44:47], v[160:163], v[212:215], v[44:47]
	v_mfma_f32_16x16x32_bf16 v[40:43], v[182:185], v[212:215], v[40:43]
	v_mfma_f32_16x16x32_bf16 v[28:31], v[160:163], v[220:223], v[28:31]
	v_mfma_f32_16x16x32_bf16 v[24:27], v[182:185], v[220:223], v[24:27]
	v_mfma_f32_16x16x32_bf16 v[12:15], v[160:163], v[228:231], v[12:15]
	v_mfma_f32_16x16x32_bf16 v[8:11], v[182:185], v[228:231], v[8:11]
	v_mfma_f32_16x16x32_bf16 v[60:63], v[178:181], v[194:197], v[60:63]
	v_mfma_f32_16x16x32_bf16 v[56:59], v[186:189], v[194:197], v[56:59]
	v_mfma_f32_16x16x32_bf16 v[44:47], v[178:181], v[216:219], v[44:47]
	v_mfma_f32_16x16x32_bf16 v[40:43], v[186:189], v[216:219], v[40:43]
	s_setprio 2
	s_barrier
; #define PG8_STAGE(bufoff, gbase, voff) do { _Pragma("unroll") for (int _i = 0; _i < 2; ++_i) \
;         __builtin_amdgcn_global_load_lds((const unsigned*)((const char*)(gbase) + (voff)[_i]), (PG8_LAS unsigned*)(lds + (bufoff) + ldsw + _i * 8192), 16, 0, 0); } while (0)
; #define PG8_LDA(dst, b, h) do { _Pragma("unroll") for (int m = 0; m < 4; ++m) _Pragma("unroll") for (int k = 0; k < 2; ++k) dst[m][k] = *(const PG8_LAS bf16x8*)(lds + PG8_SA(b, h) + aoff + m * 2048 + k * 1024); } while (0)
; #define PG8_LDB(dst, b, h) do { _Pragma("unroll") for (int n = 0; n < 2; ++n) _Pragma("unroll") for (int k = 0; k < 2; ++k) dst[n][k] = *(const PG8_LAS bf16x8*)(lds + PG8_SB(b, h) + boff + n * 2048 + k * 1024); } while (0)
; #define PG8_MMA(ai, bj, At, Bt) do { __builtin_amdgcn_s_setprio(1); _Pragma("unroll") for (int m = 0; m < 4; ++m) _Pragma("unroll") for (int n = 0; n < 2; ++n) _Pragma("unroll") for (int k = 0; k < 2; ++k) \
;         acc[ai][bj][m][n] = __builtin_amdgcn_mfma_f32_16x16x32_bf16(Bt[n][k], At[m][k], acc[ai][bj][m][n], 0, 0, 0); __builtin_amdgcn_s_setprio(0); } while (0)
; #define PG8_WAIT_V(n) asm volatile("s_waitcnt vmcnt(" #n ")" ::: "memory")
; #define PG8_WAIT_L(n) asm volatile("s_waitcnt lgkmcnt(" #n ")" ::: "memory")
; #define PG8_BAR __builtin_amdgcn_s_barrier()
; #define PG8_SCHED __builtin_amdgcn_sched_barrier(0)
; template <class Epi, class Sched, bool ALIGN_EPI = false, bool SP2 = false>
; __device__ __forceinline__ void gemm_phase(PG8_LAS unsigned char* lds, const Gemm g, const Sched& S, const Epi& E) {
;     ...
;             PG8_WAIT_V(8); PG8_WAIT_L(0); PG8_BAR; PG8_MMA(1, 0, At, B0); PG8_MMA(1, 1, At, B1); PG8_BAR; PG8_SCHED;
;             PG8_LDB(B0, 1, 0); PG8_LDB(B1, 1, 1); PG8_SCHED; PG8_LDA(At, 1, 0); PG8_STAGE(PG8_SA(0, 1), a2 + hstep, voffA);
;             PG8_WAIT_V(8); PG8_WAIT_L(0); PG8_BAR; PG8_MMA(0, 0, At, B0); PG8_MMA(0, 1, At, B1); PG8_BAR; PG8_SCHED;
	v_mfma_f32_16x16x32_bf16 v[28:31], v[178:181], v[224:227], v[28:31]
	v_mfma_f32_16x16x32_bf16 v[24:27], v[186:189], v[224:227], v[24:27]
	v_mfma_f32_16x16x32_bf16 v[12:15], v[178:181], v[232:235], v[12:15]
	v_mfma_f32_16x16x32_bf16 v[8:11], v[186:189], v[232:235], v[8:11]
	s_setprio 0
	s_add_i32 s18, 0, 0x18000
	v_add_u32_e32 v137, s18, v200
	ds_read_b128 v[144:147], v137
	ds_read_b128 v[148:151], v137 offset:1024
	ds_read_b128 v[152:155], v137 offset:2048
	ds_read_b128 v[156:159], v137 offset:3072
	v_add_u32_e32 v137, s33, v200
	ds_read_b128 v[160:163], v137
	ds_read_b128 v[178:181], v137 offset:1024
	ds_read_b128 v[182:185], v137 offset:2048
	ds_read_b128 v[186:189], v137 offset:3072
	s_add_u32 s16, s28, s12
	s_addc_u32 s17, s29, 0
	s_mov_b32 m0, s54
	v_lshl_add_u64 v[246:247], s[16:17], 0, v[0:1]
	ds_read_b128 v[190:193], v210 offset:32768
	ds_read_b128 v[194:197], v210 offset:33792
	ds_read_b128 v[212:215], v210 offset:34816
	ds_read_b128 v[216:219], v210 offset:35840
	ds_read_b128 v[220:223], v210 offset:36864
	ds_read_b128 v[224:227], v210 offset:37888
	ds_read_b128 v[228:231], v210 offset:38912
	ds_read_b128 v[232:235], v210 offset:39936
	global_load_lds_dwordx4 v[246:247], off
	v_lshl_add_u64 v[246:247], s[16:17], 0, v[2:3]
	s_mov_b32 m0, s55
	s_nop 0
	global_load_lds_dwordx4 v[246:247], off
	s_waitcnt vmcnt(8)
	s_waitcnt lgkmcnt(0)
	s_barrier
	s_setprio 1
	s_waitcnt lgkmcnt(0)
	v_mfma_f32_16x16x32_bf16 v[132:135], v[144:147], v[190:193], v[132:135]
	v_mfma_f32_16x16x32_bf16 v[128:131], v[152:155], v[190:193], v[128:131]
	v_mfma_f32_16x16x32_bf16 v[116:119], v[144:147], v[212:215], v[116:119]
	v_mfma_f32_16x16x32_bf16 v[112:115], v[152:155], v[212:215], v[112:115]
	v_mfma_f32_16x16x32_bf16 v[100:103], v[144:147], v[220:223], v[100:103]
	v_mfma_f32_16x16x32_bf16 v[96:99], v[152:155], v[220:223], v[96:99]
	v_mfma_f32_16x16x32_bf16 v[84:87], v[144:147], v[228:231], v[84:87]
	v_mfma_f32_16x16x32_bf16 v[80:83], v[152:155], v[228:231], v[80:83]
	v_mfma_f32_16x16x32_bf16 v[132:135], v[148:151], v[194:197], v[132:135]
	v_mfma_f32_16x16x32_bf16 v[128:131], v[156:159], v[194:197], v[128:131]
	v_mfma_f32_16x16x32_bf16 v[116:119], v[148:151], v[216:219], v[116:119]
	v_mfma_f32_16x16x32_bf16 v[112:115], v[156:159], v[216:219], v[112:115]
	v_mfma_f32_16x16x32_bf16 v[100:103], v[148:151], v[224:227], v[100:103]
	v_mfma_f32_16x16x32_bf16 v[96:99], v[156:159], v[224:227], v[96:99]
	v_mfma_f32_16x16x32_bf16 v[84:87], v[148:151], v[232:235], v[84:87]
	v_mfma_f32_16x16x32_bf16 v[80:83], v[156:159], v[232:235], v[80:83]
	s_setprio 0
	s_setprio 1
	v_mfma_f32_16x16x32_bf16 v[124:127], v[160:163], v[190:193], v[124:127]
	v_mfma_f32_16x16x32_bf16 v[120:123], v[182:185], v[190:193], v[120:123]
	v_mfma_f32_16x16x32_bf16 v[108:111], v[160:163], v[212:215], v[108:111]
	v_mfma_f32_16x16x32_bf16 v[104:107], v[182:185], v[212:215], v[104:107]
	v_mfma_f32_16x16x32_bf16 v[92:95], v[160:163], v[220:223], v[92:95]
	v_mfma_f32_16x16x32_bf16 v[88:91], v[182:185], v[220:223], v[88:91]
	v_mfma_f32_16x16x32_bf16 v[76:79], v[160:163], v[228:231], v[76:79]
	v_mfma_f32_16x16x32_bf16 v[72:75], v[182:185], v[228:231], v[72:75]
	v_mfma_f32_16x16x32_bf16 v[124:127], v[178:181], v[194:197], v[124:127]
	v_mfma_f32_16x16x32_bf16 v[120:123], v[186:189], v[194:197], v[120:123]
	v_mfma_f32_16x16x32_bf16 v[108:111], v[178:181], v[216:219], v[108:111]
	v_mfma_f32_16x16x32_bf16 v[104:107], v[186:189], v[216:219], v[104:107]
	s_setprio 2
	s_barrier
; #define PG8_STAGE(bufoff, gbase, voff) do { _Pragma("unroll") for (int _i = 0; _i < 2; ++_i) \
;         __builtin_amdgcn_global_load_lds((const unsigned*)((const char*)(gbase) + (voff)[_i]), (PG8_LAS unsigned*)(lds + (bufoff) + ldsw + _i * 8192), 16, 0, 0); } while (0)
; #define PG8_LDA(dst, b, h) do { _Pragma("unroll") for (int m = 0; m < 4; ++m) _Pragma("unroll") for (int k = 0; k < 2; ++k) dst[m][k] = *(const PG8_LAS bf16x8*)(lds + PG8_SA(b, h) + aoff + m * 2048 + k * 1024); } while (0)
; #define PG8_MMA(ai, bj, At, Bt) do { __builtin_amdgcn_s_setprio(1); _Pragma("unroll") for (int m = 0; m < 4; ++m) _Pragma("unroll") for (int n = 0; n < 2; ++n) _Pragma("unroll") for (int k = 0; k < 2; ++k) \
;         acc[ai][bj][m][n] = __builtin_amdgcn_mfma_f32_16x16x32_bf16(Bt[n][k], At[m][k], acc[ai][bj][m][n], 0, 0, 0); __builtin_amdgcn_s_setprio(0); } while (0)
; #define PG8_WAIT_V(n) asm volatile("s_waitcnt vmcnt(" #n ")" ::: "memory")
; #define PG8_WAIT_L(n) asm volatile("s_waitcnt lgkmcnt(" #n ")" ::: "memory")
; #define PG8_BAR __builtin_amdgcn_s_barrier()
; #define PG8_SCHED __builtin_amdgcn_sched_barrier(0)
; template <class Epi, class Sched, bool ALIGN_EPI = false, bool SP2 = false>
; __device__ __forceinline__ void gemm_phase(PG8_LAS unsigned char* lds, const Gemm g, const Sched& S, const Epi& E) {
;     ...
;         for (int t = 0; t < nt; t += 2) {
;             const bool last = (t == nt - 2);
;             const char* a1 = cA + (size_t)(t + 1) * kstep;
;             const char* a2 = last ? nA : cA + (size_t)(t + 2) * kstep; const char* b2 = last ? nB : cB + (size_t)(t + 2) * kstep;
;             const char* a3 = a2 + kstep; const char* b3 = b2 + kstep;
;     ...
;             PG8_WAIT_V(8); PG8_WAIT_L(0); PG8_BAR; PG8_MMA(0, 0, At, B0); PG8_MMA(0, 1, At, B1); PG8_BAR; PG8_SCHED;
;             PG8_LDA(At, 1, 1); PG8_STAGE(PG8_SB(1, 0), b3, voffB); PG8_STAGE(PG8_SB(1, 1), b3 + hstep, voffB); PG8_STAGE(PG8_SA(1, 0), a3, voffA);
;             PG8_WAIT_V(8); PG8_WAIT_L(0); PG8_BAR; PG8_MMA(1, 0, At, B0); PG8_MMA(1, 1, At, B1); PG8_BAR; PG8_SCHED;
	v_mfma_f32_16x16x32_bf16 v[92:95], v[178:181], v[224:227], v[92:95]
	v_mfma_f32_16x16x32_bf16 v[88:91], v[186:189], v[224:227], v[88:91]
	v_mfma_f32_16x16x32_bf16 v[76:79], v[178:181], v[232:235], v[76:79]
	v_mfma_f32_16x16x32_bf16 v[72:75], v[186:189], v[232:235], v[72:75]
	s_setprio 0
	s_add_i32 s16, s18, s41
	v_lshl_add_u64 v[198:199], v[198:199], 0, s[20:21]
	s_mov_b32 m0, s16
	ds_read_b128 v[190:193], v210 offset:49152
	ds_read_b128 v[194:197], v210 offset:50176
	ds_read_b128 v[212:215], v210 offset:51200
	ds_read_b128 v[216:219], v210 offset:52224
	ds_read_b128 v[220:223], v210 offset:53248
	ds_read_b128 v[224:227], v210 offset:54272
	ds_read_b128 v[228:231], v210 offset:55296
	ds_read_b128 v[232:235], v210 offset:56320
	global_load_lds_dwordx4 v[198:199], off
	v_lshl_add_u64 v[198:199], v[236:237], 0, s[20:21]
	s_add_i32 m0, s16, 0x2000
	s_add_i32 s16, s33, s41
	global_load_lds_dwordx4 v[198:199], off
	v_lshl_add_u64 v[198:199], v[238:239], 0, s[20:21]
	s_mov_b32 m0, s16
	s_nop 0
	global_load_lds_dwordx4 v[198:199], off
	v_lshl_add_u64 v[198:199], v[240:241], 0, s[20:21]
	s_add_i32 m0, s16, 0x2000
	s_nop 0
	global_load_lds_dwordx4 v[198:199], off
	v_lshl_add_u64 v[198:199], v[242:243], 0, s[20:21]
	v_lshl_add_u64 v[244:245], v[244:245], 0, s[20:21]
	s_waitcnt vmcnt(6)
	s_waitcnt lgkmcnt(0)
	s_barrier
	s_setprio 1
	s_waitcnt lgkmcnt(0)
	v_mfma_f32_16x16x32_bf16 v[68:71], v[144:147], v[190:193], v[68:71]
	v_mfma_f32_16x16x32_bf16 v[64:67], v[152:155], v[190:193], v[64:67]
	v_mfma_f32_16x16x32_bf16 v[52:55], v[144:147], v[212:215], v[52:55]
	s_mov_b32 m0, s56
	v_mfma_f32_16x16x32_bf16 v[48:51], v[152:155], v[212:215], v[48:51]
	global_load_lds_dwordx4 v[198:199], off
	v_mfma_f32_16x16x32_bf16 v[36:39], v[144:147], v[220:223], v[36:39]
	v_mfma_f32_16x16x32_bf16 v[32:35], v[152:155], v[220:223], v[32:35]
	v_mfma_f32_16x16x32_bf16 v[20:23], v[144:147], v[228:231], v[20:23]
	s_add_u32 s24, s24, 0x100
	s_addc_u32 s25, s25, 0
	v_mfma_f32_16x16x32_bf16 v[16:19], v[152:155], v[228:231], v[16:19]
	s_add_u32 s23, s23, 0x100
	s_addc_u32 s35, s35, 0
	v_mfma_f32_16x16x32_bf16 v[68:71], v[148:151], v[194:197], v[68:71]
	s_add_u32 s16, s24, 0x80
	s_addc_u32 s17, s25, 0
	v_mfma_f32_16x16x32_bf16 v[64:67], v[156:159], v[194:197], v[64:67]
	s_cmp_eq_u32 s60, s36
	s_cselect_b32 s29, s3, s17
	s_cselect_b32 s28, s2, s16
	v_mfma_f32_16x16x32_bf16 v[52:55], v[148:151], v[216:219], v[52:55]
	s_cselect_b32 s17, s9, s35
	s_cselect_b32 s16, s8, s23
	s_mov_b32 m0, s57
	v_mfma_f32_16x16x32_bf16 v[48:51], v[156:159], v[216:219], v[48:51]
	s_add_i32 s36, s36, 2
	global_load_lds_dwordx4 v[244:245], off
	v_mfma_f32_16x16x32_bf16 v[36:39], v[148:151], v[224:227], v[36:39]
	v_mfma_f32_16x16x32_bf16 v[32:35], v[156:159], v[224:227], v[32:35]
	v_mfma_f32_16x16x32_bf16 v[20:23], v[148:151], v[232:235], v[20:23]
	v_mfma_f32_16x16x32_bf16 v[16:19], v[156:159], v[232:235], v[16:19]
	s_setprio 0
	s_setprio 1
	v_mfma_f32_16x16x32_bf16 v[60:63], v[160:163], v[190:193], v[60:63]
	v_mfma_f32_16x16x32_bf16 v[56:59], v[182:185], v[190:193], v[56:59]
	v_mfma_f32_16x16x32_bf16 v[44:47], v[160:163], v[212:215], v[44:47]
	v_mfma_f32_16x16x32_bf16 v[40:43], v[182:185], v[212:215], v[40:43]
	v_mfma_f32_16x16x32_bf16 v[28:31], v[160:163], v[220:223], v[28:31]
	v_mfma_f32_16x16x32_bf16 v[24:27], v[182:185], v[220:223], v[24:27]
	v_mfma_f32_16x16x32_bf16 v[12:15], v[160:163], v[228:231], v[12:15]
	v_mfma_f32_16x16x32_bf16 v[8:11], v[182:185], v[228:231], v[8:11]
	v_mfma_f32_16x16x32_bf16 v[60:63], v[178:181], v[194:197], v[60:63]
	v_mfma_f32_16x16x32_bf16 v[56:59], v[186:189], v[194:197], v[56:59]
	v_mfma_f32_16x16x32_bf16 v[44:47], v[178:181], v[216:219], v[44:47]
	v_mfma_f32_16x16x32_bf16 v[40:43], v[186:189], v[216:219], v[40:43]
	s_setprio 2
	s_barrier
	v_mfma_f32_16x16x32_bf16 v[28:31], v[178:181], v[224:227], v[28:31]
	v_mfma_f32_16x16x32_bf16 v[24:27], v[186:189], v[224:227], v[24:27]
	v_mfma_f32_16x16x32_bf16 v[12:15], v[178:181], v[232:235], v[12:15]
	v_mfma_f32_16x16x32_bf16 v[8:11], v[186:189], v[232:235], v[8:11]
	s_setprio 0
	s_add_i32 s18, s59, 2
	s_cmp_ge_u32 s36, s18
	s_cbranch_scc0 .LBB0_203
	s_and_b64 vcc, exec, s[46:47]
	s_cbranch_vccz .LBB0_206
	s_barrier
	s_setprio 1

; #define PG8_STAGE(bufoff, gbase, voff) do { _Pragma("unroll") for (int _i = 0; _i < 2; ++_i) \
;         __builtin_amdgcn_global_load_lds((const unsigned*)((const char*)(gbase) + (voff)[_i]), (PG8_LAS unsigned*)(lds + (bufoff) + ldsw + _i * 8192), 16, 0, 0); } while (0)
; #define PG8_LDA(dst, b, h) do { _Pragma("unroll") for (int m = 0; m < 4; ++m) _Pragma("unroll") for (int k = 0; k < 2; ++k) dst[m][k] = *(const PG8_LAS bf16x8*)(lds + PG8_SA(b, h) + aoff + m * 2048 + k * 1024); } while (0)
; #define PG8_LDB(dst, b, h) do { _Pragma("unroll") for (int n = 0; n < 2; ++n) _Pragma("unroll") for (int k = 0; k < 2; ++k) dst[n][k] = *(const PG8_LAS bf16x8*)(lds + PG8_SB(b, h) + boff + n * 2048 + k * 1024); } while (0)
; #define PG8_MMA(ai, bj, At, Bt) do { __builtin_amdgcn_s_setprio(1); _Pragma("unroll") for (int m = 0; m < 4; ++m) _Pragma("unroll") for (int n = 0; n < 2; ++n) _Pragma("unroll") for (int k = 0; k < 2; ++k) \
;         acc[ai][bj][m][n] = __builtin_amdgcn_mfma_f32_16x16x32_bf16(Bt[n][k], At[m][k], acc[ai][bj][m][n], 0, 0, 0); __builtin_amdgcn_s_setprio(0); } while (0)
; #define PG8_WAIT_V(n) asm volatile("s_waitcnt vmcnt(" #n ")" ::: "memory")
; #define PG8_WAIT_L(n) asm volatile("s_waitcnt lgkmcnt(" #n ")" ::: "memory")
; #define PG8_BAR __builtin_amdgcn_s_barrier()
; #define PG8_SCHED __builtin_amdgcn_sched_barrier(0)
; template <class Epi, class Sched, bool ALIGN_EPI = false, bool SP2 = false>
; __device__ __forceinline__ void gemm_phase(PG8_LAS unsigned char* lds, const Gemm g, const Sched& S, const Epi& E) {
;     ...
;             PG8_LDB(B0, 0, 0); PG8_LDB(B1, 0, 1); PG8_SCHED; PG8_LDA(At, 0, 0); PG8_STAGE(PG8_SA(1, 1), a1 + hstep, voffA);
;             PG8_WAIT_V(8); PG8_WAIT_L(0); PG8_BAR; PG8_MMA(0, 0, At, B0); PG8_MMA(0, 1, At, B1); PG8_BAR; PG8_SCHED;
;             PG8_LDA(At, 0, 1); PG8_STAGE(PG8_SB(0, 0), b2, voffB); PG8_STAGE(PG8_SB(0, 1), b2 + hstep, voffB); PG8_STAGE(PG8_SA(0, 0), a2, voffA);
;             PG8_WAIT_V(8); PG8_WAIT_L(0); PG8_BAR; PG8_MMA(1, 0, At, B0); PG8_MMA(1, 1, At, B1); PG8_BAR; PG8_SCHED;
.LBB0_257:
	s_add_i32 s18, 0, 0x10000
	v_add_u32_e32 v0, s18, v210
	s_add_i32 s19, 0, 0x14000
	ds_read_b128 v[104:107], v0
	ds_read_b128 v[140:143], v0 offset:1024
	ds_read_b128 v[144:147], v0 offset:2048
	ds_read_b128 v[148:151], v0 offset:3072
	v_add_u32_e32 v0, s19, v210
	ds_read_b128 v[152:155], v0
	ds_read_b128 v[156:159], v0 offset:1024
	ds_read_b128 v[160:163], v0 offset:2048
	ds_read_b128 v[192:195], v0 offset:3072
	v_lshl_add_u64 v[2:3], s[8:9], 0, v[188:189]
	s_add_i32 m0, s44, 0xc000
	ds_read_b128 v[196:199], v212
	ds_read_b128 v[214:217], v212 offset:1024
	ds_read_b128 v[218:221], v212 offset:2048
	ds_read_b128 v[222:225], v212 offset:3072
	ds_read_b128 v[226:229], v212 offset:4096
	ds_read_b128 v[230:233], v212 offset:5120
	ds_read_b128 v[234:237], v212 offset:6144
	ds_read_b128 v[238:241], v212 offset:7168
	global_load_lds_dwordx4 v[2:3], off
	v_lshl_add_u64 v[2:3], s[8:9], 0, v[190:191]
	s_add_i32 m0, s44, 0xe000
	s_nop 0
	global_load_lds_dwordx4 v[2:3], off
	s_waitcnt vmcnt(8)
	s_waitcnt lgkmcnt(0)
	s_barrier
	s_setprio 1
	s_waitcnt lgkmcnt(0)
	v_mfma_f32_16x16x32_bf16 v[136:139], v[104:107], v[196:199], v[136:139]
	v_mfma_f32_16x16x32_bf16 v[128:131], v[144:147], v[196:199], v[128:131]
	v_mfma_f32_16x16x32_bf16 v[120:123], v[104:107], v[218:221], v[120:123]
	v_mfma_f32_16x16x32_bf16 v[112:115], v[144:147], v[218:221], v[112:115]
	v_mfma_f32_16x16x32_bf16 v[100:103], v[104:107], v[226:229], v[100:103]
	v_mfma_f32_16x16x32_bf16 v[92:95], v[144:147], v[226:229], v[92:95]
	v_mfma_f32_16x16x32_bf16 v[84:87], v[104:107], v[234:237], v[84:87]
	v_mfma_f32_16x16x32_bf16 v[76:79], v[144:147], v[234:237], v[76:79]
	v_mfma_f32_16x16x32_bf16 v[136:139], v[140:143], v[214:217], v[136:139]
	v_mfma_f32_16x16x32_bf16 v[128:131], v[148:151], v[214:217], v[128:131]
	v_mfma_f32_16x16x32_bf16 v[120:123], v[140:143], v[222:225], v[120:123]
	v_mfma_f32_16x16x32_bf16 v[112:115], v[148:151], v[222:225], v[112:115]
	v_mfma_f32_16x16x32_bf16 v[100:103], v[140:143], v[230:233], v[100:103]
	v_mfma_f32_16x16x32_bf16 v[92:95], v[148:151], v[230:233], v[92:95]
	v_mfma_f32_16x16x32_bf16 v[84:87], v[140:143], v[238:241], v[84:87]
	v_mfma_f32_16x16x32_bf16 v[76:79], v[148:151], v[238:241], v[76:79]
	s_setprio 0
	s_setprio 1
	v_mfma_f32_16x16x32_bf16 v[132:135], v[152:155], v[196:199], v[132:135]
	v_mfma_f32_16x16x32_bf16 v[124:127], v[160:163], v[196:199], v[124:127]
	v_mfma_f32_16x16x32_bf16 v[116:119], v[152:155], v[218:221], v[116:119]
	v_mfma_f32_16x16x32_bf16 v[108:111], v[160:163], v[218:221], v[108:111]
	v_mfma_f32_16x16x32_bf16 v[96:99], v[152:155], v[226:229], v[96:99]
	v_mfma_f32_16x16x32_bf16 v[88:91], v[160:163], v[226:229], v[88:91]
	v_mfma_f32_16x16x32_bf16 v[80:83], v[152:155], v[234:237], v[80:83]
	v_mfma_f32_16x16x32_bf16 v[72:75], v[160:163], v[234:237], v[72:75]
	v_mfma_f32_16x16x32_bf16 v[132:135], v[156:159], v[214:217], v[132:135]
	v_mfma_f32_16x16x32_bf16 v[124:127], v[192:195], v[214:217], v[124:127]
	v_mfma_f32_16x16x32_bf16 v[116:119], v[156:159], v[222:225], v[116:119]
	v_mfma_f32_16x16x32_bf16 v[108:111], v[192:195], v[222:225], v[108:111]
	s_setprio 2
	s_barrier
	v_mfma_f32_16x16x32_bf16 v[96:99], v[156:159], v[230:233], v[96:99]
	v_mfma_f32_16x16x32_bf16 v[88:91], v[192:195], v[230:233], v[88:91]
	v_mfma_f32_16x16x32_bf16 v[80:83], v[156:159], v[238:241], v[80:83]
	v_mfma_f32_16x16x32_bf16 v[72:75], v[192:195], v[238:241], v[72:75]
	s_setprio 0
	s_add_i32 s16, s18, s36
	v_lshl_add_u64 v[2:3], s[40:41], 0, v[182:183]
	s_mov_b32 m0, s16
	ds_read_b128 v[196:199], v212 offset:16384
	ds_read_b128 v[214:217], v212 offset:17408
	ds_read_b128 v[218:221], v212 offset:18432
	ds_read_b128 v[222:225], v212 offset:19456
	ds_read_b128 v[226:229], v212 offset:20480
	ds_read_b128 v[230:233], v212 offset:21504
	ds_read_b128 v[234:237], v212 offset:22528
	ds_read_b128 v[238:241], v212 offset:23552
	global_load_lds_dwordx4 v[2:3], off
	s_add_i32 m0, s16, 0x2000
	s_add_u32 s16, s40, 0x40000
	v_lshl_add_u64 v[200:201], s[40:41], 0, v[178:179]
	s_addc_u32 s17, s41, 0
	s_add_i32 s18, s19, s36
	global_load_lds_dwordx4 v[200:201], off
	v_lshl_add_u64 v[242:243], s[16:17], 0, v[182:183]
	s_mov_b32 m0, s18
	v_lshl_add_u64 v[244:245], s[42:43], 0, v[180:181]
	global_load_lds_dwordx4 v[242:243], off
	v_lshl_add_u64 v[242:243], s[16:17], 0, v[178:179]
	s_add_i32 m0, s18, 0x2000
	s_nop 0
	global_load_lds_dwordx4 v[242:243], off
	v_lshl_add_u64 v[242:243], s[42:43], 0, v[184:185]
	s_waitcnt vmcnt(6)
	s_waitcnt lgkmcnt(0)
	s_barrier
	s_setprio 1
	s_waitcnt lgkmcnt(0)
	v_mfma_f32_16x16x32_bf16 v[68:71], v[104:107], v[196:199], v[68:71]
	v_mfma_f32_16x16x32_bf16 v[60:63], v[144:147], v[196:199], v[60:63]
	v_mfma_f32_16x16x32_bf16 v[52:55], v[104:107], v[218:221], v[52:55]
	s_mov_b32 m0, s44
	v_mfma_f32_16x16x32_bf16 v[44:47], v[144:147], v[218:221], v[44:47]
	global_load_lds_dwordx4 v[242:243], off
	v_mfma_f32_16x16x32_bf16 v[36:39], v[104:107], v[226:229], v[36:39]
	v_mfma_f32_16x16x32_bf16 v[28:31], v[144:147], v[226:229], v[28:31]
	v_mfma_f32_16x16x32_bf16 v[20:23], v[104:107], v[234:237], v[20:23]
	v_mfma_f32_16x16x32_bf16 v[12:15], v[144:147], v[234:237], v[12:15]
	v_mfma_f32_16x16x32_bf16 v[68:71], v[140:143], v[214:217], v[68:71]
	v_mfma_f32_16x16x32_bf16 v[60:63], v[148:151], v[214:217], v[60:63]
	v_mfma_f32_16x16x32_bf16 v[52:55], v[140:143], v[222:225], v[52:55]
	s_mov_b32 m0, s45
	v_mfma_f32_16x16x32_bf16 v[44:47], v[148:151], v[222:225], v[44:47]
	global_load_lds_dwordx4 v[244:245], off
	v_mfma_f32_16x16x32_bf16 v[36:39], v[140:143], v[230:233], v[36:39]
	v_mfma_f32_16x16x32_bf16 v[28:31], v[148:151], v[230:233], v[28:31]
	v_mfma_f32_16x16x32_bf16 v[20:23], v[140:143], v[238:241], v[20:23]
	v_mfma_f32_16x16x32_bf16 v[12:15], v[148:151], v[238:241], v[12:15]
	s_setprio 0
	s_setprio 1
	v_mfma_f32_16x16x32_bf16 v[64:67], v[152:155], v[196:199], v[64:67]
	v_mfma_f32_16x16x32_bf16 v[56:59], v[160:163], v[196:199], v[56:59]
	v_mfma_f32_16x16x32_bf16 v[48:51], v[152:155], v[218:221], v[48:51]
	v_mfma_f32_16x16x32_bf16 v[40:43], v[160:163], v[218:221], v[40:43]
	v_mfma_f32_16x16x32_bf16 v[32:35], v[152:155], v[226:229], v[32:35]
	v_mfma_f32_16x16x32_bf16 v[24:27], v[160:163], v[226:229], v[24:27]
	v_mfma_f32_16x16x32_bf16 v[16:19], v[152:155], v[234:237], v[16:19]
	v_mfma_f32_16x16x32_bf16 v[8:11], v[160:163], v[234:237], v[8:11]
	v_mfma_f32_16x16x32_bf16 v[64:67], v[156:159], v[214:217], v[64:67]
	v_mfma_f32_16x16x32_bf16 v[56:59], v[192:195], v[214:217], v[56:59]
	v_mfma_f32_16x16x32_bf16 v[48:51], v[156:159], v[222:225], v[48:51]
	v_mfma_f32_16x16x32_bf16 v[40:43], v[192:195], v[222:225], v[40:43]
	s_setprio 2
	s_barrier
; #define PG8_STAGE(bufoff, gbase, voff) do { _Pragma("unroll") for (int _i = 0; _i < 2; ++_i) \
;         __builtin_amdgcn_global_load_lds((const unsigned*)((const char*)(gbase) + (voff)[_i]), (PG8_LAS unsigned*)(lds + (bufoff) + ldsw + _i * 8192), 16, 0, 0); } while (0)
; #define PG8_LDA(dst, b, h) do { _Pragma("unroll") for (int m = 0; m < 4; ++m) _Pragma("unroll") for (int k = 0; k < 2; ++k) dst[m][k] = *(const PG8_LAS bf16x8*)(lds + PG8_SA(b, h) + aoff + m * 2048 + k * 1024); } while (0)
; #define PG8_LDB(dst, b, h) do { _Pragma("unroll") for (int n = 0; n < 2; ++n) _Pragma("unroll") for (int k = 0; k < 2; ++k) dst[n][k] = *(const PG8_LAS bf16x8*)(lds + PG8_SB(b, h) + boff + n * 2048 + k * 1024); } while (0)
; #define PG8_MMA(ai, bj, At, Bt) do { __builtin_amdgcn_s_setprio(1); _Pragma("unroll") for (int m = 0; m < 4; ++m) _Pragma("unroll") for (int n = 0; n < 2; ++n) _Pragma("unroll") for (int k = 0; k < 2; ++k) \
;         acc[ai][bj][m][n] = __builtin_amdgcn_mfma_f32_16x16x32_bf16(Bt[n][k], At[m][k], acc[ai][bj][m][n], 0, 0, 0); __builtin_amdgcn_s_setprio(0); } while (0)
; #define PG8_WAIT_V(n) asm volatile("s_waitcnt vmcnt(" #n ")" ::: "memory")
; #define PG8_WAIT_L(n) asm volatile("s_waitcnt lgkmcnt(" #n ")" ::: "memory")
; #define PG8_BAR __builtin_amdgcn_s_barrier()
; #define PG8_SCHED __builtin_amdgcn_sched_barrier(0)
; template <class Epi, class Sched, bool ALIGN_EPI = false, bool SP2 = false>
; __device__ __forceinline__ void gemm_phase(PG8_LAS unsigned char* lds, const Gemm g, const Sched& S, const Epi& E) {
;     ...
;             PG8_WAIT_V(8); PG8_WAIT_L(0); PG8_BAR; PG8_MMA(1, 0, At, B0); PG8_MMA(1, 1, At, B1); PG8_BAR; PG8_SCHED;
;             PG8_LDB(B0, 1, 0); PG8_LDB(B1, 1, 1); PG8_SCHED; PG8_LDA(At, 1, 0); PG8_STAGE(PG8_SA(0, 1), a2 + hstep, voffA);
;             PG8_WAIT_V(8); PG8_WAIT_L(0); PG8_BAR; PG8_MMA(0, 0, At, B0); PG8_MMA(0, 1, At, B1); PG8_BAR; PG8_SCHED;
	v_mfma_f32_16x16x32_bf16 v[32:35], v[156:159], v[230:233], v[32:35]
	v_mfma_f32_16x16x32_bf16 v[24:27], v[192:195], v[230:233], v[24:27]
	v_mfma_f32_16x16x32_bf16 v[16:19], v[156:159], v[238:241], v[16:19]
	v_mfma_f32_16x16x32_bf16 v[8:11], v[192:195], v[238:241], v[8:11]
	s_setprio 0
	s_add_i32 s18, 0, 0x18000
	v_add_u32_e32 v0, s18, v210
	ds_read_b128 v[104:107], v0
	ds_read_b128 v[140:143], v0 offset:1024
	ds_read_b128 v[144:147], v0 offset:2048
	ds_read_b128 v[148:151], v0 offset:3072
	v_add_u32_e32 v0, s33, v210
	ds_read_b128 v[152:155], v0
	ds_read_b128 v[156:159], v0 offset:1024
	ds_read_b128 v[160:163], v0 offset:2048
	ds_read_b128 v[192:195], v0 offset:3072
	s_add_u32 s16, s42, 0x40000
	s_addc_u32 s17, s43, 0
	s_mov_b32 m0, s46
	v_lshl_add_u64 v[246:247], s[16:17], 0, v[184:185]
	ds_read_b128 v[196:199], v212 offset:32768
	ds_read_b128 v[214:217], v212 offset:33792
	ds_read_b128 v[218:221], v212 offset:34816
	ds_read_b128 v[222:225], v212 offset:35840
	ds_read_b128 v[226:229], v212 offset:36864
	ds_read_b128 v[230:233], v212 offset:37888
	ds_read_b128 v[234:237], v212 offset:38912
	ds_read_b128 v[238:241], v212 offset:39936
	global_load_lds_dwordx4 v[246:247], off
	v_lshl_add_u64 v[246:247], s[16:17], 0, v[180:181]
	s_mov_b32 m0, s47
	s_nop 0
	global_load_lds_dwordx4 v[246:247], off
	s_waitcnt vmcnt(8)
	s_waitcnt lgkmcnt(0)
	s_barrier
	s_setprio 1
	s_waitcnt lgkmcnt(0)
	v_mfma_f32_16x16x32_bf16 v[136:139], v[104:107], v[196:199], v[136:139]
	v_mfma_f32_16x16x32_bf16 v[128:131], v[144:147], v[196:199], v[128:131]
	v_mfma_f32_16x16x32_bf16 v[120:123], v[104:107], v[218:221], v[120:123]
	v_mfma_f32_16x16x32_bf16 v[112:115], v[144:147], v[218:221], v[112:115]
	v_mfma_f32_16x16x32_bf16 v[100:103], v[104:107], v[226:229], v[100:103]
	v_mfma_f32_16x16x32_bf16 v[92:95], v[144:147], v[226:229], v[92:95]
	v_mfma_f32_16x16x32_bf16 v[84:87], v[104:107], v[234:237], v[84:87]
	v_mfma_f32_16x16x32_bf16 v[76:79], v[144:147], v[234:237], v[76:79]
	v_mfma_f32_16x16x32_bf16 v[136:139], v[140:143], v[214:217], v[136:139]
	v_mfma_f32_16x16x32_bf16 v[128:131], v[148:151], v[214:217], v[128:131]
	v_mfma_f32_16x16x32_bf16 v[120:123], v[140:143], v[222:225], v[120:123]
	v_mfma_f32_16x16x32_bf16 v[112:115], v[148:151], v[222:225], v[112:115]
	v_mfma_f32_16x16x32_bf16 v[100:103], v[140:143], v[230:233], v[100:103]
	v_mfma_f32_16x16x32_bf16 v[92:95], v[148:151], v[230:233], v[92:95]
	v_mfma_f32_16x16x32_bf16 v[84:87], v[140:143], v[238:241], v[84:87]
	v_mfma_f32_16x16x32_bf16 v[76:79], v[148:151], v[238:241], v[76:79]
	s_setprio 0
	s_setprio 1
	v_mfma_f32_16x16x32_bf16 v[132:135], v[152:155], v[196:199], v[132:135]
	v_mfma_f32_16x16x32_bf16 v[124:127], v[160:163], v[196:199], v[124:127]
	v_mfma_f32_16x16x32_bf16 v[116:119], v[152:155], v[218:221], v[116:119]
	v_mfma_f32_16x16x32_bf16 v[108:111], v[160:163], v[218:221], v[108:111]
	v_mfma_f32_16x16x32_bf16 v[96:99], v[152:155], v[226:229], v[96:99]
	v_mfma_f32_16x16x32_bf16 v[88:91], v[160:163], v[226:229], v[88:91]
	v_mfma_f32_16x16x32_bf16 v[80:83], v[152:155], v[234:237], v[80:83]
	v_mfma_f32_16x16x32_bf16 v[72:75], v[160:163], v[234:237], v[72:75]
	v_mfma_f32_16x16x32_bf16 v[132:135], v[156:159], v[214:217], v[132:135]
	v_mfma_f32_16x16x32_bf16 v[124:127], v[192:195], v[214:217], v[124:127]
	v_mfma_f32_16x16x32_bf16 v[116:119], v[156:159], v[222:225], v[116:119]
	v_mfma_f32_16x16x32_bf16 v[108:111], v[192:195], v[222:225], v[108:111]
	s_setprio 2
	s_barrier
; #define PG8_STAGE(bufoff, gbase, voff) do { _Pragma("unroll") for (int _i = 0; _i < 2; ++_i) \
;         __builtin_amdgcn_global_load_lds((const unsigned*)((const char*)(gbase) + (voff)[_i]), (PG8_LAS unsigned*)(lds + (bufoff) + ldsw + _i * 8192), 16, 0, 0); } while (0)
; #define PG8_LDA(dst, b, h) do { _Pragma("unroll") for (int m = 0; m < 4; ++m) _Pragma("unroll") for (int k = 0; k < 2; ++k) dst[m][k] = *(const PG8_LAS bf16x8*)(lds + PG8_SA(b, h) + aoff + m * 2048 + k * 1024); } while (0)
; #define PG8_MMA(ai, bj, At, Bt) do { __builtin_amdgcn_s_setprio(1); _Pragma("unroll") for (int m = 0; m < 4; ++m) _Pragma("unroll") for (int n = 0; n < 2; ++n) _Pragma("unroll") for (int k = 0; k < 2; ++k) \
;         acc[ai][bj][m][n] = __builtin_amdgcn_mfma_f32_16x16x32_bf16(Bt[n][k], At[m][k], acc[ai][bj][m][n], 0, 0, 0); __builtin_amdgcn_s_setprio(0); } while (0)
; #define PG8_WAIT_V(n) asm volatile("s_waitcnt vmcnt(" #n ")" ::: "memory")
; #define PG8_WAIT_L(n) asm volatile("s_waitcnt lgkmcnt(" #n ")" ::: "memory")
; #define PG8_BAR __builtin_amdgcn_s_barrier()
; #define PG8_SCHED __builtin_amdgcn_sched_barrier(0)
; template <class Epi, class Sched, bool ALIGN_EPI = false, bool SP2 = false>
; __device__ __forceinline__ void gemm_phase(PG8_LAS unsigned char* lds, const Gemm g, const Sched& S, const Epi& E) {
;     ...
;         for (int t = 0; t < nt; t += 2) {
;             const bool last = (t == nt - 2);
;             const char* a1 = cA + (size_t)(t + 1) * kstep;
;             const char* a2 = last ? nA : cA + (size_t)(t + 2) * kstep; const char* b2 = last ? nB : cB + (size_t)(t + 2) * kstep;
;             const char* a3 = a2 + kstep; const char* b3 = b2 + kstep;
;     ...
;             PG8_WAIT_V(8); PG8_WAIT_L(0); PG8_BAR; PG8_MMA(0, 0, At, B0); PG8_MMA(0, 1, At, B1); PG8_BAR; PG8_SCHED;
;             PG8_LDA(At, 1, 1); PG8_STAGE(PG8_SB(1, 0), b3, voffB); PG8_STAGE(PG8_SB(1, 1), b3 + hstep, voffB); PG8_STAGE(PG8_SA(1, 0), a3, voffA);
;             PG8_WAIT_V(8); PG8_WAIT_L(0); PG8_BAR; PG8_MMA(1, 0, At, B0); PG8_MMA(1, 1, At, B1); PG8_BAR; PG8_SCHED;
	v_mfma_f32_16x16x32_bf16 v[96:99], v[156:159], v[230:233], v[96:99]
	v_mfma_f32_16x16x32_bf16 v[88:91], v[192:195], v[230:233], v[88:91]
	v_mfma_f32_16x16x32_bf16 v[80:83], v[156:159], v[238:241], v[80:83]
	v_mfma_f32_16x16x32_bf16 v[72:75], v[192:195], v[238:241], v[72:75]
	s_setprio 0
	s_add_i32 s16, s18, s36
	v_lshl_add_u64 v[2:3], v[2:3], 0, s[20:21]
	s_mov_b32 m0, s16
	ds_read_b128 v[196:199], v212 offset:49152
	ds_read_b128 v[214:217], v212 offset:50176
	ds_read_b128 v[218:221], v212 offset:51200
	ds_read_b128 v[222:225], v212 offset:52224
	ds_read_b128 v[226:229], v212 offset:53248
	ds_read_b128 v[230:233], v212 offset:54272
	ds_read_b128 v[234:237], v212 offset:55296
	ds_read_b128 v[238:241], v212 offset:56320
	global_load_lds_dwordx4 v[2:3], off
	s_add_i32 m0, s16, 0x2000
	s_add_u32 s16, s40, 0x40080
	v_lshl_add_u64 v[2:3], v[200:201], 0, s[20:21]
	s_addc_u32 s17, s41, 0
	s_add_i32 s18, s33, s36
	global_load_lds_dwordx4 v[2:3], off
	v_lshl_add_u64 v[2:3], s[16:17], 0, v[182:183]
	s_mov_b32 m0, s18
	s_nop 0
	global_load_lds_dwordx4 v[2:3], off
	v_lshl_add_u64 v[2:3], s[16:17], 0, v[178:179]
	s_add_i32 m0, s18, 0x2000
	s_nop 0
	global_load_lds_dwordx4 v[2:3], off
	v_lshl_add_u64 v[2:3], v[242:243], 0, s[20:21]
	v_lshl_add_u64 v[244:245], v[244:245], 0, s[20:21]
	s_waitcnt vmcnt(6)
	s_waitcnt lgkmcnt(0)
	s_barrier
	s_setprio 1
	s_waitcnt lgkmcnt(0)
	v_mfma_f32_16x16x32_bf16 v[68:71], v[104:107], v[196:199], v[68:71]
	v_mfma_f32_16x16x32_bf16 v[60:63], v[144:147], v[196:199], v[60:63]
	v_mfma_f32_16x16x32_bf16 v[52:55], v[104:107], v[218:221], v[52:55]
	s_mov_b32 m0, s48
	v_mfma_f32_16x16x32_bf16 v[44:47], v[144:147], v[218:221], v[44:47]
	global_load_lds_dwordx4 v[2:3], off
	v_mfma_f32_16x16x32_bf16 v[36:39], v[104:107], v[226:229], v[36:39]
	v_mfma_f32_16x16x32_bf16 v[28:31], v[144:147], v[226:229], v[28:31]
	v_mfma_f32_16x16x32_bf16 v[20:23], v[104:107], v[234:237], v[20:23]
	s_add_i32 s55, s55, 2
	v_mfma_f32_16x16x32_bf16 v[12:15], v[144:147], v[234:237], v[12:15]
	s_add_u32 s8, s8, 0x100
	s_addc_u32 s9, s9, 0
	v_mfma_f32_16x16x32_bf16 v[68:71], v[140:143], v[214:217], v[68:71]
	s_add_u32 s53, s53, 0x100
	s_addc_u32 s54, s54, 0
	v_mfma_f32_16x16x32_bf16 v[60:63], v[148:151], v[214:217], v[60:63]
	s_add_u32 s16, s8, 0xfffc0080
	s_addc_u32 s17, s9, -1
	v_mfma_f32_16x16x32_bf16 v[52:55], v[140:143], v[222:225], v[52:55]
	s_cmp_eq_u32 s55, 12
	s_cselect_b32 s43, s14, s17
	s_cselect_b32 s42, s15, s16
	s_mov_b32 m0, s49
	v_mfma_f32_16x16x32_bf16 v[44:47], v[148:151], v[222:225], v[44:47]
	s_cselect_b32 s41, s13, s54
	s_cselect_b32 s40, s25, s53
	global_load_lds_dwordx4 v[244:245], off
	v_mfma_f32_16x16x32_bf16 v[36:39], v[140:143], v[230:233], v[36:39]
	v_mfma_f32_16x16x32_bf16 v[28:31], v[148:151], v[230:233], v[28:31]
	v_mfma_f32_16x16x32_bf16 v[20:23], v[140:143], v[238:241], v[20:23]
	v_mfma_f32_16x16x32_bf16 v[12:15], v[148:151], v[238:241], v[12:15]
	s_setprio 0
	s_setprio 1
	v_mfma_f32_16x16x32_bf16 v[64:67], v[152:155], v[196:199], v[64:67]
	v_mfma_f32_16x16x32_bf16 v[56:59], v[160:163], v[196:199], v[56:59]
	v_mfma_f32_16x16x32_bf16 v[48:51], v[152:155], v[218:221], v[48:51]
	v_mfma_f32_16x16x32_bf16 v[40:43], v[160:163], v[218:221], v[40:43]
	v_mfma_f32_16x16x32_bf16 v[32:35], v[152:155], v[226:229], v[32:35]
	v_mfma_f32_16x16x32_bf16 v[24:27], v[160:163], v[226:229], v[24:27]
	v_mfma_f32_16x16x32_bf16 v[16:19], v[152:155], v[234:237], v[16:19]
	v_mfma_f32_16x16x32_bf16 v[8:11], v[160:163], v[234:237], v[8:11]
	v_mfma_f32_16x16x32_bf16 v[64:67], v[156:159], v[214:217], v[64:67]
	v_mfma_f32_16x16x32_bf16 v[56:59], v[192:195], v[214:217], v[56:59]
	v_mfma_f32_16x16x32_bf16 v[48:51], v[156:159], v[222:225], v[48:51]
	v_mfma_f32_16x16x32_bf16 v[40:43], v[192:195], v[222:225], v[40:43]
	s_setprio 2
	s_barrier
	v_mfma_f32_16x16x32_bf16 v[32:35], v[156:159], v[230:233], v[32:35]
	v_mfma_f32_16x16x32_bf16 v[24:27], v[192:195], v[230:233], v[24:27]
	v_mfma_f32_16x16x32_bf16 v[16:19], v[156:159], v[238:241], v[16:19]
	v_mfma_f32_16x16x32_bf16 v[8:11], v[192:195], v[238:241], v[8:11]
	s_setprio 0
	s_cmp_gt_u32 s55, 13
	s_cbranch_scc0 .LBB0_257
	s_and_b64 vcc, exec, s[10:11]
	s_cbranch_vccz .LBB0_260
	s_barrier
	s_setprio 1
